# GDN pre conv: the three look-back inputs fetched together with the first token loads, one wait instead of three serial round trips
# speedup vs baseline: 1.0503x; 1.0035x over previous
; template <class F> DI void gdn_conv(const Prm& p, int kind, int b, int c, int col, int t0, int n, F f) {
;     f32x2 w[4];
; #pragma unroll
;     for (int j = 0; j < 4; ++j) w[j] = (f32x2){p.conv_w[j * 1536 + col], p.conv_w[j * 1536 + col + 1]};
;     f32x2 x0 = gdn_raw(p, kind, b, c, t0 - 3, col), x1 = gdn_raw(p, kind, b, c, t0 - 2, col), x2 = gdn_raw(p, kind, b, c, t0 - 1, col);
; DI void gdn_pre_unit(const Prm& p, unsigned char* lds0, int u, int tid, int wid, int lane) {
;     ...
;     const float gl = gL[63];
;     if (wid < 6) { const int part = wid % 3, th = wid / 3;
;         gdn_conv(p, kind, b, c, part * 512 + h * 128 + 2 * lane, 32 * th, 32, [&](int t, float y0, float y1) {
.LBB0_1158:
	v_cmp_ne_u32_e64 s[4:5], 1, v38
	s_andn2_b64 vcc, exec, s[26:27]
	s_waitcnt lgkmcnt(0)
	s_barrier
	s_cbranch_vccnz .LBB0_1365
	s_mov_b32 s98, 0
	s_mov_b32 s99, 0
	s_mov_b32 s100, 0
	s_add_i32 s0, s58, 0x1c4fc
	v_mov_b32_e32 v0, s0
	s_lshl_b32 s0, s94, 7
	v_readlane_b32 s1, v246, 18
	s_add_i32 s0, s0, s1
	v_lshl_add_u32 v12, v34, 1, s0
	v_readlane_b32 s8, v247, 44
	v_ashrrev_i32_e32 v13, 31, v12
	v_readlane_b32 s18, v247, 54
	v_readlane_b32 s19, v247, 55
	ds_read_b32 v27, v0
	v_readlane_b32 s9, v247, 45
	v_lshl_add_u64 v[6:7], v[12:13], 2, s[18:19]
	v_add_co_u32_e32 v2, vcc, 0x1000, v6
	global_load_dwordx2 v[0:1], v[6:7], off
	s_nop 0
	v_addc_co_u32_e32 v3, vcc, 0, v7, vcc
	v_add_co_u32_e32 v4, vcc, 0x3000, v6
	global_load_dwordx2 v[2:3], v[2:3], off offset:2048
	s_nop 0
	v_addc_co_u32_e32 v5, vcc, 0, v7, vcc
	global_load_dwordx2 v[4:5], v[4:5], off
	v_add_co_u32_e32 v6, vcc, 0x4000, v6
	v_readlane_b32 s10, v247, 46
	s_nop 0
	v_addc_co_u32_e32 v7, vcc, 0, v7, vcc
	global_load_dwordx2 v[6:7], v[6:7], off offset:2048
	s_mov_b64 s[8:9], -1
	s_mov_b64 s[0:1], 0
	s_and_b64 vcc, exec, s[68:69]
	s_mul_hi_i32 s52, s79, 3
	s_mul_i32 s89, s79, 3
	s_mov_b64 s[6:7], 0
	v_readlane_b32 s11, v247, 47
	v_readlane_b32 s12, v247, 48
	v_readlane_b32 s13, v247, 49
	v_readlane_b32 s14, v247, 50
	v_readlane_b32 s15, v247, 51
	v_readlane_b32 s16, v247, 52
	v_readlane_b32 s17, v247, 53
	v_readlane_b32 s20, v247, 56
	v_readlane_b32 s21, v247, 57
	v_readlane_b32 s22, v247, 58
	v_readlane_b32 s23, v247, 59
	s_cbranch_vccz .LBB0_1165
	s_and_b64 vcc, exec, s[62:63]
	s_cbranch_vccz .LBB0_1162
	s_lshl_b32 s6, s79, 6
	s_add_i32 s10, s6, 0x8000
	s_mov_b64 s[6:7], -1
	s_cbranch_execz .LBB0_1163
	s_branch .LBB0_1164

; DI float bflo(unsigned u) { return __uint_as_float(u << 16); }
; DI float bfhi(unsigned u) { return __uint_as_float(u & 0xffff0000u); }
; DI f32x2 gdn_raw(const Prm& p, int kind, int b, int c, int t_rel, int col) {
;     const bf16_t* HP = (const bf16_t*)(p.ws + W_HP); int row;
;     if (kind == 0) {
;         if (t_rel < 0) { if (c == 0) return (f32x2){0.f, 0.f}; const unsigned u = *(const unsigned*)((const bf16_t*)(p.ws + W_HALO) + (((size_t)b * 129 + c) * 3 + (3 + t_rel)) * 1536 + col); return (f32x2){bflo(u), bfhi(u)}; }
;         row = c == 0 ? ROW_META + 16 * b + t_rel : b * 8192 + 64 * (c - 1) + t_rel;
;     } else {
;         if (t_rel < 0) { const float* s = p.state_conv + ((size_t)b * 3 + (3 + t_rel)) * 1536 + col; return (f32x2){s[0], s[1]}; }
;         row = ROW_S + 64 * b + t_rel;
;     }
;     const unsigned u = *(const unsigned*)(HP + (size_t)row * NPJ + col); return (f32x2){bflo(u), bfhi(u)};
; template <class F> DI void gdn_conv(const Prm& p, int kind, int b, int c, int col, int t0, int n, F f) {
;     ...
;     f32x2 x0 = gdn_raw(p, kind, b, c, t0 - 3, col), x1 = gdn_raw(p, kind, b, c, t0 - 2, col), x2 = gdn_raw(p, kind, b, c, t0 - 1, col);
.LBB0_1171:
	s_and_b64 vcc, exec, s[6:7]
	s_cbranch_vccz .LBB0_1173
	v_readlane_b32 s6, v246, 19
	s_add_i32 s6, s6, s10
	s_mul_hi_i32 s7, s6, 0x1600
	s_mulk_i32 s6, 0x1600
	v_readlane_b32 s8, v247, 62
	v_readlane_b32 s9, v247, 63
	s_add_u32 s6, s8, s6
	s_addc_u32 s7, s9, s7
	v_lshl_add_u64 v[8:9], v[12:13], 1, s[6:7]
	global_load_dword v100, v[8:9], off
	s_mov_b32 s98, 1
.LBB0_1173:
	s_andn2_b64 vcc, exec, s[0:1]
	s_mul_hi_i32 s10, s79, 0x81
	s_mul_i32 s11, s79, 0x81
	s_cbranch_vccnz .LBB0_1176
	v_readlane_b32 s0, v246, 61
	v_readlane_b32 s1, v246, 62
	s_waitcnt vmcnt(0)
	v_mov_b32_e32 v19, 0
	s_andn2_b64 vcc, exec, s[0:1]
	v_mov_b32_e32 v18, 0
	s_mov_b32 s98, 0
	s_cbranch_vccnz .LBB0_1176
	s_ashr_i32 s0, s95, 31
	s_add_u32 s1, s11, s95
	s_addc_u32 s0, s10, s0
	s_mul_i32 s0, s0, 3
	s_mul_hi_u32 s6, s1, 3
	s_add_i32 s6, s6, s0
	s_mul_i32 s1, s1, 3
	s_add_u32 s0, s1, s71
	s_addc_u32 s1, s6, s87
	s_mulk_i32 s1, 0xc00
	s_mul_hi_u32 s6, s0, 0xc00
	s_add_i32 s6, s6, s1
	s_mulk_i32 s0, 0xc00
	s_add_u32 s0, s16, s0
	s_addc_u32 s1, s17, s6
	v_lshl_add_u64 v[8:9], v[12:13], 1, s[0:1]
	global_load_dword v100, v[8:9], off
	s_mov_b32 s98, 1

; DI float bflo(unsigned u) { return __uint_as_float(u << 16); }
; DI float bfhi(unsigned u) { return __uint_as_float(u & 0xffff0000u); }
; DI f32x2 gdn_raw(const Prm& p, int kind, int b, int c, int t_rel, int col) {
;     const bf16_t* HP = (const bf16_t*)(p.ws + W_HP); int row;
;     if (kind == 0) {
;         if (t_rel < 0) { if (c == 0) return (f32x2){0.f, 0.f}; const unsigned u = *(const unsigned*)((const bf16_t*)(p.ws + W_HALO) + (((size_t)b * 129 + c) * 3 + (3 + t_rel)) * 1536 + col); return (f32x2){bflo(u), bfhi(u)}; }
;         row = c == 0 ? ROW_META + 16 * b + t_rel : b * 8192 + 64 * (c - 1) + t_rel;
;     } else {
;         if (t_rel < 0) { const float* s = p.state_conv + ((size_t)b * 3 + (3 + t_rel)) * 1536 + col; return (f32x2){s[0], s[1]}; }
;         row = ROW_S + 64 * b + t_rel;
;     }
;     const unsigned u = *(const unsigned*)(HP + (size_t)row * NPJ + col); return (f32x2){bflo(u), bfhi(u)};
; template <class F> DI void gdn_conv(const Prm& p, int kind, int b, int c, int col, int t0, int n, F f) {
;     ...
;     f32x2 x0 = gdn_raw(p, kind, b, c, t0 - 3, col), x1 = gdn_raw(p, kind, b, c, t0 - 2, col), x2 = gdn_raw(p, kind, b, c, t0 - 1, col);
.LBB0_1188:
	s_and_b64 vcc, exec, s[6:7]
	s_cbranch_vccz .LBB0_1190
	v_readlane_b32 s6, v246, 22
	s_add_i32 s6, s6, s12
	s_mul_hi_i32 s7, s6, 0x1600
	s_mulk_i32 s6, 0x1600
	v_readlane_b32 s8, v247, 62
	v_readlane_b32 s9, v247, 63
	s_add_u32 s6, s8, s6
	s_addc_u32 s7, s9, s7
	v_lshl_add_u64 v[8:9], v[12:13], 1, s[6:7]
	global_load_dword v101, v[8:9], off
	s_mov_b32 s99, 1
.LBB0_1190:
	s_andn2_b64 vcc, exec, s[0:1]
	s_cbranch_vccnz .LBB0_1193
	v_readlane_b32 s0, v246, 63
	v_readlane_b32 s1, v241, 0
	s_waitcnt vmcnt(0)
	v_mov_b32_e32 v21, 0
	s_andn2_b64 vcc, exec, s[0:1]
	v_mov_b32_e32 v20, 0
	s_mov_b32 s99, 0
	s_cbranch_vccnz .LBB0_1193
	s_ashr_i32 s0, s95, 31
	s_add_u32 s1, s11, s95
	s_addc_u32 s0, s10, s0
	s_mul_i32 s0, s0, 3
	s_mul_hi_u32 s6, s1, 3
	s_add_i32 s6, s6, s0
	s_mul_i32 s1, s1, 3
	v_readlane_b32 s0, v246, 23
	s_add_u32 s0, s1, s0
	v_readlane_b32 s1, v246, 24
	s_addc_u32 s1, s6, s1
	s_mulk_i32 s1, 0xc00
	s_mul_hi_u32 s6, s0, 0xc00
	s_add_i32 s6, s6, s1
	s_mulk_i32 s0, 0xc00
	s_add_u32 s0, s16, s0
	s_addc_u32 s1, s17, s6
	v_lshl_add_u64 v[8:9], v[12:13], 1, s[0:1]
	global_load_dword v101, v[8:9], off
	s_mov_b32 s99, 1

; DI float siluf(float x) { return x * __builtin_amdgcn_rcpf(1.f + __expf(-x)); }
; template <class F> DI void gdn_conv(const Prm& p, int kind, int b, int c, int col, int t0, int n, F f) {
;     ...
;     f32x2 x0 = gdn_raw(p, kind, b, c, t0 - 3, col), x1 = gdn_raw(p, kind, b, c, t0 - 2, col), x2 = gdn_raw(p, kind, b, c, t0 - 1, col);
; #pragma unroll 8
;     for (int t = t0; t < t0 + n; ++t) { const f32x2 x3 = gdn_raw(p, kind, b, c, t, col);
;         const float y0 = w[0].x * x0.x + w[1].x * x1.x + w[2].x * x2.x + w[3].x * x3.x, y1 = w[0].y * x0.y + w[1].y * x1.y + w[2].y * x2.y + w[3].y * x3.y;
;         f(t, siluf(y0), siluf(y1)); x0 = x1; x1 = x2; x2 = x3; }
.LBB0_1205:
	s_and_b64 vcc, exec, s[6:7]
	s_cbranch_vccz .LBB0_1207
	v_readlane_b32 s6, v246, 25
	s_add_i32 s6, s6, s12
	s_mul_hi_i32 s7, s6, 0x1600
	s_mulk_i32 s6, 0x1600
	v_readlane_b32 s8, v247, 62
	v_readlane_b32 s9, v247, 63
	s_add_u32 s6, s8, s6
	s_addc_u32 s7, s9, s7
	v_lshl_add_u64 v[8:9], v[12:13], 1, s[6:7]
	global_load_dword v102, v[8:9], off
	s_mov_b32 s100, 1
.LBB0_1207:
	s_mov_b64 s[20:21], s[24:25]
	s_andn2_b64 vcc, exec, s[0:1]
	s_cbranch_vccnz .LBB0_1210
	v_readlane_b32 s0, v241, 1
	v_readlane_b32 s1, v241, 2
	s_waitcnt vmcnt(0)
	v_mov_b32_e32 v23, 0
	s_andn2_b64 vcc, exec, s[0:1]
	v_mov_b32_e32 v22, 0
	s_mov_b32 s100, 0
	s_cbranch_vccnz .LBB0_1210
	s_ashr_i32 s0, s95, 31
	s_add_u32 s1, s11, s95
	s_addc_u32 s0, s10, s0
	s_mul_i32 s0, s0, 3
	s_mul_hi_u32 s6, s1, 3
	s_add_i32 s6, s6, s0
	s_mul_i32 s1, s1, 3
	v_readlane_b32 s0, v246, 26
	s_add_u32 s0, s1, s0
	v_readlane_b32 s1, v246, 27
	s_addc_u32 s1, s6, s1
	s_mulk_i32 s1, 0xc00
	s_mul_hi_u32 s6, s0, 0xc00
	s_add_i32 s6, s6, s1
	s_mulk_i32 s0, 0xc00
	s_add_u32 s0, s16, s0
	s_addc_u32 s1, s17, s6
	v_lshl_add_u64 v[8:9], v[12:13], 1, s[0:1]
	global_load_dword v102, v[8:9], off
	s_mov_b32 s100, 1
.LBB0_1210:
	s_lshl_b32 s53, s79, 6
	s_add_i32 s53, s53, 0x8000
	s_cmp_lg_u32 s95, 0
	s_cselect_b64 s[0:1], -1, 0
	s_lshl_b32 s6, s79, 13
	s_lshl_b32 s7, s95, 6
	s_add_i32 s6, s6, s7
	s_lshl_b32 s7, s79, 4
	s_sub_i32 s6, s6, 64
	s_add_i32 s7, s7, 0x8800
	s_ashr_i32 s8, s95, 31
	s_add_u32 s9, s11, s95
	s_addc_u32 s8, s10, s8
	s_mul_i32 s8, s8, 3
	s_mul_hi_u32 s10, s9, 3
	s_add_i32 s14, s10, s8
	s_cmp_eq_u32 s95, 0
	s_cselect_b32 s24, s7, s6
	s_movk_i32 s6, 0x120
	v_mul_lo_u32 v24, v34, s6
	v_readlane_b32 s6, v246, 54
	s_mul_i32 s15, s9, 3
	s_mul_i32 s7, s79, 0x122400
	v_add_u32_e32 v28, s6, v24
	v_readlane_b32 s6, v246, 55
	s_mul_i32 s9, s95, 0x2400
	s_mul_hi_i32 s8, s95, 0x2400
	v_lshl_add_u32 v29, v34, 2, s6
	s_mul_hi_i32 s6, s79, 0x122400
	s_add_u32 s7, s7, s9
	s_addc_u32 s8, s6, s8
	v_readlane_b32 s6, v246, 57
	v_readlane_b32 s10, v247, 62
	s_add_u32 s6, s6, s7
	v_readlane_b32 s7, v246, 58
	v_lshlrev_b64 v[14:15], 1, v[12:13]
	v_readlane_b32 s11, v247, 63
	s_addc_u32 s7, s7, s8
	v_lshl_add_u64 v[10:11], s[16:17], 0, v[14:15]
	v_lshl_add_u64 v[8:9], s[10:11], 0, v[14:15]
	v_lshl_add_u64 v[14:15], s[6:7], 0, v[14:15]
	s_mul_i32 s6, s79, 0x4800
	v_readlane_b32 s8, v246, 59
	v_readlane_b32 s36, v247, 11
	s_mul_hi_i32 s7, s79, 0x4800
	s_add_u32 s6, s8, s6
	v_readlane_b32 s8, v246, 60
	v_lshlrev_b64 v[16:17], 2, v[12:13]
	v_readlane_b32 s46, v247, 21
	v_readlane_b32 s47, v247, 22
	s_addc_u32 s7, s8, s7
	s_mov_b64 s[92:93], 0
	v_lshl_add_u64 v[12:13], s[46:47], 0, v[16:17]
	v_lshl_add_u64 v[16:17], s[6:7], 0, v[16:17]
	v_readlane_b32 s25, v246, 56
	v_readlane_b32 s37, v247, 12
	v_readlane_b32 s38, v247, 13
	v_readlane_b32 s39, v247, 14
	v_readlane_b32 s40, v247, 15
	v_readlane_b32 s41, v247, 16
	v_readlane_b32 s42, v247, 17
	v_readlane_b32 s43, v247, 18
	v_readlane_b32 s44, v247, 19
	v_readlane_b32 s45, v247, 20
	v_readlane_b32 s48, v247, 23
	v_readlane_b32 s49, v247, 24
	v_readlane_b32 s50, v247, 25
	v_readlane_b32 s51, v247, 26
	s_cmp_lg_u64 s[68:69], 0
	s_cselect_b32 s32, s53, s24
	s_add_i32 s32, s32, s71
	v_mad_u64_u32 v[68:69], s[6:7], s32, v40, v[8:9]
	global_load_dword v60, v[68:69], off
	s_add_i32 s32, s32, 1
	v_mad_u64_u32 v[68:69], s[6:7], s32, v40, v[8:9]
	global_load_dword v61, v[68:69], off
	s_add_i32 s32, s32, 1
	v_mad_u64_u32 v[68:69], s[6:7], s32, v40, v[8:9]
	global_load_dword v62, v[68:69], off
	s_add_i32 s32, s32, 1
	v_mad_u64_u32 v[68:69], s[6:7], s32, v40, v[8:9]
	global_load_dword v63, v[68:69], off
	s_add_i32 s32, s32, 1
	v_mad_u64_u32 v[68:69], s[6:7], s32, v40, v[8:9]
	global_load_dword v64, v[68:69], off
	s_add_i32 s32, s32, 1
	v_mad_u64_u32 v[68:69], s[6:7], s32, v40, v[8:9]
	global_load_dword v65, v[68:69], off
	s_add_i32 s32, s32, 1
	v_mad_u64_u32 v[68:69], s[6:7], s32, v40, v[8:9]
	global_load_dword v66, v[68:69], off
	s_add_i32 s32, s32, 1
	v_mad_u64_u32 v[68:69], s[6:7], s32, v40, v[8:9]
	global_load_dword v67, v[68:69], off
	s_waitcnt vmcnt(8)
	s_cmp_eq_u32 s98, 0
	s_cbranch_scc1 .Lcv_skip0
	v_lshlrev_b32_e32 v18, 16, v100
	v_and_b32_e32 v19, 0xffff0000, v100
.Lcv_skip0:
	s_cmp_eq_u32 s99, 0
	s_cbranch_scc1 .Lcv_skip1
	v_lshlrev_b32_e32 v20, 16, v101
	v_and_b32_e32 v21, 0xffff0000, v101
.Lcv_skip1:
	s_cmp_eq_u32 s100, 0
	s_cbranch_scc1 .Lcv_skip2
	v_lshlrev_b32_e32 v22, 16, v102
	v_and_b32_e32 v23, 0xffff0000, v102
.Lcv_skip2:
	s_branch .LBB0_1212
.LBB0_1211:
	s_add_u32 s92, s92, 8
	s_mov_b64 s[6:7], 0x6000
	s_addc_u32 s93, s93, 0
	s_add_i32 s25, s25, 32
	v_lshl_add_u64 v[14:15], v[14:15], 0, s[6:7]
	s_mov_b64 s[6:7], 0xc000
	v_add_u32_e32 v28, 16, v28
	v_add_u32_e32 v29, 0x880, v29
	s_cmp_lg_u32 s92, 32
	v_lshl_add_u64 v[16:17], v[16:17], 0, s[6:7]
	s_cbranch_scc0 .LBB0_1364

	.amdhsa_kernel _Z5k_fwd3Prm
		.amdhsa_group_segment_fixed_size 0
		.amdhsa_private_segment_fixed_size 0
		.amdhsa_kernarg_size 496
		.amdhsa_user_sgpr_count 2
		.amdhsa_user_sgpr_dispatch_ptr 0
		.amdhsa_user_sgpr_queue_ptr 0
		.amdhsa_user_sgpr_kernarg_segment_ptr 1
		.amdhsa_user_sgpr_dispatch_id 0
		.amdhsa_user_sgpr_kernarg_preload_length 0
		.amdhsa_user_sgpr_kernarg_preload_offset 0
		.amdhsa_user_sgpr_private_segment_size 0
		.amdhsa_uses_dynamic_stack 0
		.amdhsa_enable_private_segment 0
		.amdhsa_system_sgpr_workgroup_id_x 1
		.amdhsa_system_sgpr_workgroup_id_y 0
		.amdhsa_system_sgpr_workgroup_id_z 0
		.amdhsa_system_sgpr_workgroup_info 0
		.amdhsa_system_vgpr_workitem_id 2
		.amdhsa_next_free_vgpr 256
		.amdhsa_next_free_sgpr 102
		.amdhsa_accum_offset 256
		.amdhsa_reserve_vcc 1
		.amdhsa_float_round_mode_32 0
		.amdhsa_float_round_mode_16_64 0
		.amdhsa_float_denorm_mode_32 3
		.amdhsa_float_denorm_mode_16_64 3
		.amdhsa_dx10_clamp 1
		.amdhsa_ieee_mode 1
		.amdhsa_fp16_overflow 0
		.amdhsa_tg_split 0
		.amdhsa_exception_fp_ieee_invalid_op 0
		.amdhsa_exception_fp_denorm_src 0
		.amdhsa_exception_fp_ieee_div_zero 0
		.amdhsa_exception_fp_ieee_overflow 0
		.amdhsa_exception_fp_ieee_underflow 0
		.amdhsa_exception_fp_ieee_inexact 0
		.amdhsa_exception_int_div_zero 0
	.end_amdhsa_kernel

amdhsa.kernels:
  - .agpr_count:     0
    .args:
      - .offset:         0
        .size:           240
        .value_kind:     by_value
      - .offset:         240
        .size:           4
        .value_kind:     hidden_block_count_x
      - .offset:         244
        .size:           4
        .value_kind:     hidden_block_count_y
      - .offset:         248
        .size:           4
        .value_kind:     hidden_block_count_z
      - .offset:         252
        .size:           2
        .value_kind:     hidden_group_size_x
      - .offset:         254
        .size:           2
        .value_kind:     hidden_group_size_y
      - .offset:         256
        .size:           2
        .value_kind:     hidden_group_size_z
      - .offset:         258
        .size:           2
        .value_kind:     hidden_remainder_x
      - .offset:         260
        .size:           2
        .value_kind:     hidden_remainder_y
      - .offset:         262
        .size:           2
        .value_kind:     hidden_remainder_z
      - .offset:         280
        .size:           8
        .value_kind:     hidden_global_offset_x
      - .offset:         288
        .size:           8
        .value_kind:     hidden_global_offset_y
      - .offset:         296
        .size:           8
        .value_kind:     hidden_global_offset_z
      - .offset:         304
        .size:           2
        .value_kind:     hidden_grid_dims
      - .offset:         328
        .size:           8
        .value_kind:     hidden_multigrid_sync_arg
      - .offset:         360
        .size:           4
        .value_kind:     hidden_dynamic_lds_size
    .group_segment_fixed_size: 0
    .kernarg_segment_align: 8
    .kernarg_segment_size: 496
    .language:       OpenCL C
    .language_version:
      - 2
      - 0
    .max_flat_workgroup_size: 512
    .name:           _Z5k_fwd3Prm
    .private_segment_fixed_size: 0
    .sgpr_count:     108
    .sgpr_spill_count: 153
    .symbol:         _Z5k_fwd3Prm.kd
    .uniform_work_group_size: 1
    .uses_dynamic_stack: false
    .vgpr_count:     256
    .vgpr_spill_count: 0
    .wavefront_size: 64
